# attention epilogue: 16 dwordx2 row-per-lane stores merged into 8 dwordx4 via v_permlane32_swap (on top of v19)
# speedup vs baseline: 1.0186x; 1.0019x over previous
; __device__ __forceinline__ u32x2 pack4(f32x4 v) { u32x2 r; r.x = cvt_pk(v[0], v[1]); r.y = cvt_pk(v[2], v[3]); return r; }
; __device__ __forceinline__ void attn_unit(LAS unsigned char* lds, const bf16_t* Q, const bf16_t* KN, const bf16_t* KPE, const bf16_t* VT, bf16_t* Y, float* ssq_b, int b, int h, int qg) {
;     ...
;     {
;         const float lt = lsum + __shfl_xor(lsum, 32); const float inv = 1.0f / lt;
;         const size_t row = (size_t)b * 2048 + (t0 - 16) + 32 * wid + q; float ss = 0.f;
; #pragma unroll
;         for (int db = 0; db < 4; ++db)
; #pragma unroll
;             for (int jj = 0; jj < 4; ++jj) {
;                 f32x4 v; v[0] = o[db][4 * jj] * inv; v[1] = o[db][4 * jj + 1] * inv; v[2] = o[db][4 * jj + 2] * inv; v[3] = o[db][4 * jj + 3] * inv;
;                 ss += v[0] * v[0] + v[1] * v[1] + v[2] * v[2] + v[3] * v[3];
;                 *(u32x2*)(Y + (row * 2048 + 1024 + h * 128 + 32 * db + 8 * jj + 4 * hh)) = pack4(v);
;             }
;         ss += __shfl_xor(ss, 32);
;         if (hh == 0 && ssq_b) atomicAdd(ssq_b + row, ss);
.LBB0_678:
	ds_bpermute_b32 v64, v205, v157
	s_mov_b32 s13, s17
	v_mov_b32_e32 v159, v151
	s_waitcnt vmcnt(0) lgkmcnt(0)
	s_barrier
	v_add_f32_e32 v64, v157, v64
	v_div_scale_f32 v65, s[8:9], v64, v64, 1.0
	v_rcp_f32_e32 v66, v65
	v_div_scale_f32 v67, vcc, 1.0, v64, 1.0
	v_fma_f32 v68, -v65, v66, 1.0
	v_fmac_f32_e32 v66, v68, v66
	v_mul_f32_e32 v68, v67, v66
	v_fma_f32 v69, -v65, v68, v67
	v_fmac_f32_e32 v68, v69, v66
	v_fma_f32 v65, -v65, v68, v67
	v_div_fmas_f32 v65, v65, v66, v68
	v_div_fixup_f32 v68, v65, v64, 1.0
	v_or_b32_e32 v64, s28, v149
	v_or_b32_e32 v64, s24, v64
	v_mov_b32_e32 v65, s25
	v_lshl_add_u64 v[64:65], v[64:65], 0, s[12:13]
	v_lshlrev_b64 v[66:67], 12, v[64:65]
	v_lshl_add_u64 v[66:67], s[58:59], 0, v[66:67]
	s_lshl_b32 s12, s29, 1
	v_mul_f32_e32 v49, v49, v68
	v_lshl_add_u64 v[66:67], v[66:67], 0, s[12:13]
	v_mul_f32_e32 v48, v48, v68
	v_mul_f32_e32 v69, v49, v49
	v_lshl_add_u64 v[66:67], v[66:67], 0, v[158:159]
	v_mul_f32_e32 v50, v50, v68
	v_mul_f32_e32 v51, v51, v68
	v_fmac_f32_e32 v69, v48, v48
	v_mbcnt_lo_u32_b32 v254, -1, 0
	v_mbcnt_hi_u32_b32 v254, -1, v254
	v_and_b32_e32 v254, 32, v254
	v_lshrrev_b32_e32 v254, 2, v254
	v_mov_b32_e32 v255, 0
	v_lshl_add_u64 v[252:253], v[66:67], 0, v[254:255]
	v_cvt_pk_bf16_f32 v244, v48, v49
	v_cvt_pk_bf16_f32 v245, v50, v51
	v_mul_f32_e32 v49, v53, v68
	v_fmac_f32_e32 v69, v50, v50
	v_mul_f32_e32 v48, v52, v68
	v_mul_f32_e32 v52, v49, v49
	v_fmac_f32_e32 v69, v51, v51
	v_mul_f32_e32 v50, v54, v68
	v_mul_f32_e32 v51, v55, v68
	v_fmac_f32_e32 v52, v48, v48
	v_cvt_pk_bf16_f32 v246, v48, v49
	v_cvt_pk_bf16_f32 v247, v50, v51
	s_nop 1
	v_permlane32_swap_b32_e32 v244, v246
	v_permlane32_swap_b32_e32 v245, v247
	global_store_dwordx4 v[252:253], v[244:247], off offset:2048
	v_mul_f32_e32 v49, v57, v68
	v_mul_f32_e32 v48, v56, v68
	v_mul_f32_e32 v53, v49, v49
	v_fmac_f32_e32 v52, v50, v50
	v_mul_f32_e32 v50, v58, v68
	v_fmac_f32_e32 v53, v48, v48
	v_fmac_f32_e32 v52, v51, v51
	v_mul_f32_e32 v51, v59, v68
	v_fmac_f32_e32 v53, v50, v50
	v_cvt_pk_bf16_f32 v248, v48, v49
	v_cvt_pk_bf16_f32 v249, v50, v51
	v_add_f32_e32 v52, v69, v52
	v_fmac_f32_e32 v53, v51, v51
	v_mul_f32_e32 v49, v61, v68
	v_add_f32_e32 v52, v53, v52
	v_mul_f32_e32 v48, v60, v68
	v_mul_f32_e32 v53, v49, v49
	v_fmac_f32_e32 v53, v48, v48
	v_cvt_pk_bf16_f32 v250, v48, v49
	v_mul_f32_e32 v33, v33, v68
	v_mul_f32_e32 v50, v62, v68
	v_mul_f32_e32 v51, v63, v68
	v_cvt_pk_bf16_f32 v251, v50, v51
	s_nop 1
	v_permlane32_swap_b32_e32 v248, v250
	v_permlane32_swap_b32_e32 v249, v251
	global_store_dwordx4 v[252:253], v[248:251], off offset:2080
	v_mul_f32_e32 v32, v32, v68
	v_mul_f32_e32 v48, v33, v33
	v_mul_f32_e32 v34, v34, v68
	v_mul_f32_e32 v35, v35, v68
	v_fmac_f32_e32 v48, v32, v32
	v_cvt_pk_bf16_f32 v244, v32, v33
	v_cvt_pk_bf16_f32 v245, v34, v35
	v_mul_f32_e32 v33, v37, v68
	v_fmac_f32_e32 v48, v34, v34
	v_mul_f32_e32 v32, v36, v68
	v_mul_f32_e32 v36, v33, v33
	v_fmac_f32_e32 v48, v35, v35
	v_mul_f32_e32 v34, v38, v68
	v_mul_f32_e32 v35, v39, v68
	v_fmac_f32_e32 v36, v32, v32
	v_cvt_pk_bf16_f32 v246, v32, v33
	v_cvt_pk_bf16_f32 v247, v34, v35
	v_fmac_f32_e32 v53, v50, v50
	s_nop 1
	v_permlane32_swap_b32_e32 v244, v246
	v_permlane32_swap_b32_e32 v245, v247
	global_store_dwordx4 v[252:253], v[244:247], off offset:2112
	v_mul_f32_e32 v33, v41, v68
	v_fmac_f32_e32 v53, v51, v51
	v_mul_f32_e32 v32, v40, v68
	v_mul_f32_e32 v37, v33, v33
	v_add_f32_e32 v52, v53, v52
	v_fmac_f32_e32 v36, v34, v34
	v_mul_f32_e32 v34, v42, v68
	v_fmac_f32_e32 v37, v32, v32
	v_add_f32_e32 v48, v48, v52
	v_fmac_f32_e32 v36, v35, v35
	v_mul_f32_e32 v35, v43, v68
	v_fmac_f32_e32 v37, v34, v34
	v_cvt_pk_bf16_f32 v248, v32, v33
	v_cvt_pk_bf16_f32 v249, v34, v35
	v_add_f32_e32 v36, v36, v48
	v_fmac_f32_e32 v37, v35, v35
	v_mul_f32_e32 v33, v45, v68
	v_add_f32_e32 v36, v37, v36
; __device__ __forceinline__ u32x2 pack4(f32x4 v) { u32x2 r; r.x = cvt_pk(v[0], v[1]); r.y = cvt_pk(v[2], v[3]); return r; }
; __device__ __forceinline__ void attn_unit(LAS unsigned char* lds, const bf16_t* Q, const bf16_t* KN, const bf16_t* KPE, const bf16_t* VT, bf16_t* Y, float* ssq_b, int b, int h, int qg) {
;     ...
; #pragma unroll
;         for (int db = 0; db < 4; ++db)
; #pragma unroll
;             for (int jj = 0; jj < 4; ++jj) {
;                 f32x4 v; v[0] = o[db][4 * jj] * inv; v[1] = o[db][4 * jj + 1] * inv; v[2] = o[db][4 * jj + 2] * inv; v[3] = o[db][4 * jj + 3] * inv;
;                 ss += v[0] * v[0] + v[1] * v[1] + v[2] * v[2] + v[3] * v[3];
;                 *(u32x2*)(Y + (row * 2048 + 1024 + h * 128 + 32 * db + 8 * jj + 4 * hh)) = pack4(v);
;             }
;         ss += __shfl_xor(ss, 32);
;         if (hh == 0 && ssq_b) atomicAdd(ssq_b + row, ss);
	v_mul_f32_e32 v32, v44, v68
	v_mul_f32_e32 v37, v33, v33
	v_fmac_f32_e32 v37, v32, v32
	v_cvt_pk_bf16_f32 v250, v32, v33
	v_mul_f32_e32 v17, v17, v68
	v_mul_f32_e32 v34, v46, v68
	v_mul_f32_e32 v35, v47, v68
	v_cvt_pk_bf16_f32 v251, v34, v35
	s_nop 1
	v_permlane32_swap_b32_e32 v248, v250
	v_permlane32_swap_b32_e32 v249, v251
	global_store_dwordx4 v[252:253], v[248:251], off offset:2144
	v_mul_f32_e32 v16, v16, v68
	v_mul_f32_e32 v32, v17, v17
	v_mul_f32_e32 v18, v18, v68
	v_mul_f32_e32 v19, v19, v68
	v_fmac_f32_e32 v32, v16, v16
	v_cvt_pk_bf16_f32 v244, v16, v17
	v_cvt_pk_bf16_f32 v245, v18, v19
	v_mul_f32_e32 v17, v21, v68
	v_fmac_f32_e32 v32, v18, v18
	v_mul_f32_e32 v16, v20, v68
	v_mul_f32_e32 v20, v17, v17
	v_fmac_f32_e32 v32, v19, v19
	v_mul_f32_e32 v18, v22, v68
	v_mul_f32_e32 v19, v23, v68
	v_fmac_f32_e32 v20, v16, v16
	v_cvt_pk_bf16_f32 v246, v16, v17
	v_cvt_pk_bf16_f32 v247, v18, v19
	v_fmac_f32_e32 v37, v34, v34
	s_nop 1
	v_permlane32_swap_b32_e32 v244, v246
	v_permlane32_swap_b32_e32 v245, v247
	global_store_dwordx4 v[252:253], v[244:247], off offset:2176
	v_mul_f32_e32 v17, v25, v68
	v_fmac_f32_e32 v37, v35, v35
	v_mul_f32_e32 v16, v24, v68
	v_mul_f32_e32 v21, v17, v17
	v_add_f32_e32 v36, v37, v36
	v_fmac_f32_e32 v20, v18, v18
	v_mul_f32_e32 v18, v26, v68
	v_fmac_f32_e32 v21, v16, v16
	v_add_f32_e32 v32, v32, v36
	v_fmac_f32_e32 v20, v19, v19
	v_mul_f32_e32 v19, v27, v68
	v_fmac_f32_e32 v21, v18, v18
	v_cvt_pk_bf16_f32 v248, v16, v17
	v_cvt_pk_bf16_f32 v249, v18, v19
	v_add_f32_e32 v20, v20, v32
	v_fmac_f32_e32 v21, v19, v19
	v_mul_f32_e32 v17, v29, v68
	v_add_f32_e32 v20, v21, v20
	v_mul_f32_e32 v16, v28, v68
	v_mul_f32_e32 v21, v17, v17
	v_fmac_f32_e32 v21, v16, v16
	v_cvt_pk_bf16_f32 v250, v16, v17
	v_mul_f32_e32 v1, v1, v68
	v_mul_f32_e32 v18, v30, v68
	v_mul_f32_e32 v19, v31, v68
	v_cvt_pk_bf16_f32 v251, v18, v19
	s_nop 1
	v_permlane32_swap_b32_e32 v248, v250
	v_permlane32_swap_b32_e32 v249, v251
	global_store_dwordx4 v[252:253], v[248:251], off offset:2208
	v_mul_f32_e32 v0, v0, v68
	v_mul_f32_e32 v16, v1, v1
	v_mul_f32_e32 v2, v2, v68
	v_mul_f32_e32 v3, v3, v68
	v_fmac_f32_e32 v16, v0, v0
	v_cvt_pk_bf16_f32 v244, v0, v1
	v_cvt_pk_bf16_f32 v245, v2, v3
	v_mul_f32_e32 v1, v5, v68
	v_fmac_f32_e32 v16, v2, v2
	v_mul_f32_e32 v0, v4, v68
	v_mul_f32_e32 v4, v1, v1
	v_fmac_f32_e32 v16, v3, v3
	v_mul_f32_e32 v2, v6, v68
	v_mul_f32_e32 v3, v7, v68
	v_fmac_f32_e32 v4, v0, v0
	v_cvt_pk_bf16_f32 v246, v0, v1
	v_cvt_pk_bf16_f32 v247, v2, v3
	v_fmac_f32_e32 v21, v18, v18
	s_nop 1
	v_permlane32_swap_b32_e32 v244, v246
	v_permlane32_swap_b32_e32 v245, v247
	global_store_dwordx4 v[252:253], v[244:247], off offset:2240
	v_mul_f32_e32 v1, v9, v68
	v_fmac_f32_e32 v21, v19, v19
	v_fmac_f32_e32 v4, v2, v2
	v_mul_f32_e32 v0, v8, v68
	v_mul_f32_e32 v2, v1, v1
	v_add_f32_e32 v20, v21, v20
	v_fmac_f32_e32 v4, v3, v3
	v_mul_f32_e32 v3, v10, v68
	v_fmac_f32_e32 v2, v0, v0
	v_add_f32_e32 v16, v16, v20
	v_mul_f32_e32 v5, v11, v68
	v_fmac_f32_e32 v2, v3, v3
	v_add_f32_e32 v4, v4, v16
	v_fmac_f32_e32 v2, v5, v5
	v_mul_f32_e32 v6, v13, v68
	v_add_f32_e32 v4, v2, v4
	v_cvt_pk_bf16_f32 v248, v0, v1
	v_cvt_pk_bf16_f32 v249, v3, v5
	v_mul_f32_e32 v5, v12, v68
	v_mul_f32_e32 v0, v6, v6
	v_mul_f32_e32 v7, v14, v68
	v_fmac_f32_e32 v0, v5, v5
	v_mul_f32_e32 v8, v15, v68
	v_fmac_f32_e32 v0, v7, v7
	v_fmac_f32_e32 v0, v8, v8
	v_add_f32_e32 v0, v0, v4
	ds_bpermute_b32 v1, v205, v0
	v_cvt_pk_bf16_f32 v250, v5, v6
	v_cvt_pk_bf16_f32 v251, v7, v8
	s_nop 1
	v_permlane32_swap_b32_e32 v248, v250
	v_permlane32_swap_b32_e32 v249, v251
	global_store_dwordx4 v[252:253], v[248:251], off offset:2272
	s_and_saveexec_b64 s[8:9], s[46:47]
	s_cbranch_execz .LBB0_680
	s_waitcnt lgkmcnt(0)
	v_add_f32_e32 v2, v0, v1
	v_lshl_add_u64 v[0:1], v[64:65], 2, s[62:63]
	global_atomic_add_f32 v[0:1], v2, off

; __device__ __forceinline__ u32x2 pack4(f32x4 v) { u32x2 r; r.x = cvt_pk(v[0], v[1]); r.y = cvt_pk(v[2], v[3]); return r; }
; __device__ __forceinline__ void attn_unit(LAS unsigned char* lds, const bf16_t* Q, const bf16_t* KN, const bf16_t* KPE, const bf16_t* VT, bf16_t* Y, float* ssq_b, int b, int h, int qg) {
;     ...
;     {
;         const float lt = lsum + __shfl_xor(lsum, 32); const float inv = 1.0f / lt;
;         const size_t row = (size_t)b * 2048 + (t0 - 16) + 32 * wid + q; float ss = 0.f;
; #pragma unroll
;         for (int db = 0; db < 4; ++db)
; #pragma unroll
;             for (int jj = 0; jj < 4; ++jj) {
;                 f32x4 v; v[0] = o[db][4 * jj] * inv; v[1] = o[db][4 * jj + 1] * inv; v[2] = o[db][4 * jj + 2] * inv; v[3] = o[db][4 * jj + 3] * inv;
;                 ss += v[0] * v[0] + v[1] * v[1] + v[2] * v[2] + v[3] * v[3];
;                 *(u32x2*)(Y + (row * 2048 + 1024 + h * 128 + 32 * db + 8 * jj + 4 * hh)) = pack4(v);
;             }
;         ss += __shfl_xor(ss, 32);
;         if (hh == 0 && ssq_b) atomicAdd(ssq_b + row, ss);
.LBB0_706:
	ds_bpermute_b32 v64, v205, v157
	s_mov_b32 s29, s17
	v_mov_b32_e32 v159, v151
	s_waitcnt vmcnt(0) lgkmcnt(0)
	s_barrier
	v_add_f32_e32 v64, v157, v64
	v_div_scale_f32 v65, s[6:7], v64, v64, 1.0
	v_rcp_f32_e32 v66, v65
	v_div_scale_f32 v67, vcc, 1.0, v64, 1.0
	v_fma_f32 v68, -v65, v66, 1.0
	v_fmac_f32_e32 v66, v68, v66
	v_mul_f32_e32 v68, v67, v66
	v_fma_f32 v69, -v65, v68, v67
	v_fmac_f32_e32 v68, v69, v66
	v_fma_f32 v65, -v65, v68, v67
	v_div_fmas_f32 v65, v65, v66, v68
	v_div_fixup_f32 v68, v65, v64, 1.0
	v_or_b32_e32 v64, s13, v149
	v_or_b32_e32 v64, s24, v64
	v_mov_b32_e32 v65, s25
	v_lshl_add_u64 v[64:65], v[64:65], 0, s[28:29]
	v_lshlrev_b64 v[66:67], 12, v[64:65]
	v_lshl_add_u64 v[66:67], s[58:59], 0, v[66:67]
	s_mov_b32 s13, s17
	v_mul_f32_e32 v49, v49, v68
	v_lshl_add_u64 v[66:67], v[66:67], 0, s[12:13]
	v_mul_f32_e32 v48, v48, v68
	v_mul_f32_e32 v69, v49, v49
	v_lshl_add_u64 v[66:67], v[66:67], 0, v[158:159]
	v_mul_f32_e32 v50, v50, v68
	v_mul_f32_e32 v51, v51, v68
	v_fmac_f32_e32 v69, v48, v48
	v_mbcnt_lo_u32_b32 v254, -1, 0
	v_mbcnt_hi_u32_b32 v254, -1, v254
	v_and_b32_e32 v254, 32, v254
	v_lshrrev_b32_e32 v254, 2, v254
	v_mov_b32_e32 v255, 0
	v_lshl_add_u64 v[252:253], v[66:67], 0, v[254:255]
	v_cvt_pk_bf16_f32 v244, v48, v49
	v_cvt_pk_bf16_f32 v245, v50, v51
	v_mul_f32_e32 v49, v53, v68
	v_fmac_f32_e32 v69, v50, v50
	v_mul_f32_e32 v48, v52, v68
	v_mul_f32_e32 v52, v49, v49
	v_fmac_f32_e32 v69, v51, v51
	v_mul_f32_e32 v50, v54, v68
	v_mul_f32_e32 v51, v55, v68
	v_fmac_f32_e32 v52, v48, v48
	v_cvt_pk_bf16_f32 v246, v48, v49
	v_cvt_pk_bf16_f32 v247, v50, v51
	s_nop 1
	v_permlane32_swap_b32_e32 v244, v246
	v_permlane32_swap_b32_e32 v245, v247
	global_store_dwordx4 v[252:253], v[244:247], off offset:2048
	v_mul_f32_e32 v49, v57, v68
	v_mul_f32_e32 v48, v56, v68
	v_mul_f32_e32 v53, v49, v49
	v_fmac_f32_e32 v52, v50, v50
	v_mul_f32_e32 v50, v58, v68
	v_fmac_f32_e32 v53, v48, v48
	v_fmac_f32_e32 v52, v51, v51
	v_mul_f32_e32 v51, v59, v68
	v_fmac_f32_e32 v53, v50, v50
	v_cvt_pk_bf16_f32 v248, v48, v49
	v_cvt_pk_bf16_f32 v249, v50, v51
	v_add_f32_e32 v52, v69, v52
	v_fmac_f32_e32 v53, v51, v51
	v_mul_f32_e32 v49, v61, v68
	v_add_f32_e32 v52, v53, v52
	v_mul_f32_e32 v48, v60, v68
	v_mul_f32_e32 v53, v49, v49
	v_fmac_f32_e32 v53, v48, v48
	v_cvt_pk_bf16_f32 v250, v48, v49
	v_mul_f32_e32 v33, v33, v68
	v_mul_f32_e32 v50, v62, v68
	v_mul_f32_e32 v51, v63, v68
	v_cvt_pk_bf16_f32 v251, v50, v51
	s_nop 1
	v_permlane32_swap_b32_e32 v248, v250
	v_permlane32_swap_b32_e32 v249, v251
	global_store_dwordx4 v[252:253], v[248:251], off offset:2080
	v_mul_f32_e32 v32, v32, v68
	v_mul_f32_e32 v48, v33, v33
	v_mul_f32_e32 v34, v34, v68
	v_mul_f32_e32 v35, v35, v68
	v_fmac_f32_e32 v48, v32, v32
	v_cvt_pk_bf16_f32 v244, v32, v33
	v_cvt_pk_bf16_f32 v245, v34, v35
	v_mul_f32_e32 v33, v37, v68
	v_fmac_f32_e32 v48, v34, v34
	v_mul_f32_e32 v32, v36, v68
	v_mul_f32_e32 v36, v33, v33
	v_fmac_f32_e32 v48, v35, v35
	v_mul_f32_e32 v34, v38, v68
	v_mul_f32_e32 v35, v39, v68
	v_fmac_f32_e32 v36, v32, v32
	v_cvt_pk_bf16_f32 v246, v32, v33
	v_cvt_pk_bf16_f32 v247, v34, v35
	v_fmac_f32_e32 v53, v50, v50
	s_nop 1
	v_permlane32_swap_b32_e32 v244, v246
	v_permlane32_swap_b32_e32 v245, v247
	global_store_dwordx4 v[252:253], v[244:247], off offset:2112
	v_mul_f32_e32 v33, v41, v68
	v_fmac_f32_e32 v53, v51, v51
	v_mul_f32_e32 v32, v40, v68
	v_mul_f32_e32 v37, v33, v33
	v_add_f32_e32 v52, v53, v52
	v_fmac_f32_e32 v36, v34, v34
	v_mul_f32_e32 v34, v42, v68
	v_fmac_f32_e32 v37, v32, v32
	v_add_f32_e32 v48, v48, v52
	v_fmac_f32_e32 v36, v35, v35
	v_mul_f32_e32 v35, v43, v68
	v_fmac_f32_e32 v37, v34, v34
	v_cvt_pk_bf16_f32 v248, v32, v33
	v_cvt_pk_bf16_f32 v249, v34, v35
	v_add_f32_e32 v36, v36, v48
	v_fmac_f32_e32 v37, v35, v35
	v_mul_f32_e32 v33, v45, v68
	v_add_f32_e32 v36, v37, v36
; __device__ __forceinline__ u32x2 pack4(f32x4 v) { u32x2 r; r.x = cvt_pk(v[0], v[1]); r.y = cvt_pk(v[2], v[3]); return r; }
; __device__ __forceinline__ void attn_unit(LAS unsigned char* lds, const bf16_t* Q, const bf16_t* KN, const bf16_t* KPE, const bf16_t* VT, bf16_t* Y, float* ssq_b, int b, int h, int qg) {
;     ...
; #pragma unroll
;         for (int db = 0; db < 4; ++db)
; #pragma unroll
;             for (int jj = 0; jj < 4; ++jj) {
;                 f32x4 v; v[0] = o[db][4 * jj] * inv; v[1] = o[db][4 * jj + 1] * inv; v[2] = o[db][4 * jj + 2] * inv; v[3] = o[db][4 * jj + 3] * inv;
;                 ss += v[0] * v[0] + v[1] * v[1] + v[2] * v[2] + v[3] * v[3];
;                 *(u32x2*)(Y + (row * 2048 + 1024 + h * 128 + 32 * db + 8 * jj + 4 * hh)) = pack4(v);
;             }
;         ss += __shfl_xor(ss, 32);
;         if (hh == 0 && ssq_b) atomicAdd(ssq_b + row, ss);
	v_mul_f32_e32 v32, v44, v68
	v_mul_f32_e32 v37, v33, v33
	v_fmac_f32_e32 v37, v32, v32
	v_cvt_pk_bf16_f32 v250, v32, v33
	v_mul_f32_e32 v17, v17, v68
	v_mul_f32_e32 v34, v46, v68
	v_mul_f32_e32 v35, v47, v68
	v_cvt_pk_bf16_f32 v251, v34, v35
	s_nop 1
	v_permlane32_swap_b32_e32 v248, v250
	v_permlane32_swap_b32_e32 v249, v251
	global_store_dwordx4 v[252:253], v[248:251], off offset:2144
	v_mul_f32_e32 v16, v16, v68
	v_mul_f32_e32 v32, v17, v17
	v_mul_f32_e32 v18, v18, v68
	v_mul_f32_e32 v19, v19, v68
	v_fmac_f32_e32 v32, v16, v16
	v_cvt_pk_bf16_f32 v244, v16, v17
	v_cvt_pk_bf16_f32 v245, v18, v19
	v_mul_f32_e32 v17, v21, v68
	v_fmac_f32_e32 v32, v18, v18
	v_mul_f32_e32 v16, v20, v68
	v_mul_f32_e32 v20, v17, v17
	v_fmac_f32_e32 v32, v19, v19
	v_mul_f32_e32 v18, v22, v68
	v_mul_f32_e32 v19, v23, v68
	v_fmac_f32_e32 v20, v16, v16
	v_cvt_pk_bf16_f32 v246, v16, v17
	v_cvt_pk_bf16_f32 v247, v18, v19
	v_fmac_f32_e32 v37, v34, v34
	s_nop 1
	v_permlane32_swap_b32_e32 v244, v246
	v_permlane32_swap_b32_e32 v245, v247
	global_store_dwordx4 v[252:253], v[244:247], off offset:2176
	v_mul_f32_e32 v17, v25, v68
	v_fmac_f32_e32 v37, v35, v35
	v_mul_f32_e32 v16, v24, v68
	v_mul_f32_e32 v21, v17, v17
	v_add_f32_e32 v36, v37, v36
	v_fmac_f32_e32 v20, v18, v18
	v_mul_f32_e32 v18, v26, v68
	v_fmac_f32_e32 v21, v16, v16
	v_add_f32_e32 v32, v32, v36
	v_fmac_f32_e32 v20, v19, v19
	v_mul_f32_e32 v19, v27, v68
	v_fmac_f32_e32 v21, v18, v18
	v_cvt_pk_bf16_f32 v248, v16, v17
	v_cvt_pk_bf16_f32 v249, v18, v19
	v_add_f32_e32 v20, v20, v32
	v_fmac_f32_e32 v21, v19, v19
	v_mul_f32_e32 v17, v29, v68
	v_add_f32_e32 v20, v21, v20
	v_mul_f32_e32 v16, v28, v68
	v_mul_f32_e32 v21, v17, v17
	v_fmac_f32_e32 v21, v16, v16
	v_cvt_pk_bf16_f32 v250, v16, v17
	v_mul_f32_e32 v1, v1, v68
	v_mul_f32_e32 v18, v30, v68
	v_mul_f32_e32 v19, v31, v68
	v_cvt_pk_bf16_f32 v251, v18, v19
	s_nop 1
	v_permlane32_swap_b32_e32 v248, v250
	v_permlane32_swap_b32_e32 v249, v251
	global_store_dwordx4 v[252:253], v[248:251], off offset:2208
	v_mul_f32_e32 v0, v0, v68
	v_mul_f32_e32 v16, v1, v1
	v_mul_f32_e32 v2, v2, v68
	v_mul_f32_e32 v3, v3, v68
	v_fmac_f32_e32 v16, v0, v0
	v_cvt_pk_bf16_f32 v244, v0, v1
	v_cvt_pk_bf16_f32 v245, v2, v3
	v_mul_f32_e32 v1, v5, v68
	v_fmac_f32_e32 v16, v2, v2
	v_mul_f32_e32 v0, v4, v68
	v_mul_f32_e32 v4, v1, v1
	v_fmac_f32_e32 v16, v3, v3
	v_mul_f32_e32 v2, v6, v68
	v_mul_f32_e32 v3, v7, v68
	v_fmac_f32_e32 v4, v0, v0
	v_cvt_pk_bf16_f32 v246, v0, v1
	v_cvt_pk_bf16_f32 v247, v2, v3
	v_fmac_f32_e32 v21, v18, v18
	s_nop 1
	v_permlane32_swap_b32_e32 v244, v246
	v_permlane32_swap_b32_e32 v245, v247
	global_store_dwordx4 v[252:253], v[244:247], off offset:2240
	v_mul_f32_e32 v1, v9, v68
	v_fmac_f32_e32 v21, v19, v19
	v_fmac_f32_e32 v4, v2, v2
	v_mul_f32_e32 v0, v8, v68
	v_mul_f32_e32 v2, v1, v1
	v_add_f32_e32 v20, v21, v20
	v_fmac_f32_e32 v4, v3, v3
	v_mul_f32_e32 v3, v10, v68
	v_fmac_f32_e32 v2, v0, v0
	v_add_f32_e32 v16, v16, v20
	v_mul_f32_e32 v5, v11, v68
	v_fmac_f32_e32 v2, v3, v3
	v_add_f32_e32 v4, v4, v16
	v_fmac_f32_e32 v2, v5, v5
	v_mul_f32_e32 v6, v13, v68
	v_add_f32_e32 v4, v2, v4
	v_cvt_pk_bf16_f32 v248, v0, v1
	v_cvt_pk_bf16_f32 v249, v3, v5
	v_mul_f32_e32 v5, v12, v68
	v_mul_f32_e32 v0, v6, v6
	v_mul_f32_e32 v7, v14, v68
	v_fmac_f32_e32 v0, v5, v5
	v_mul_f32_e32 v8, v15, v68
	v_fmac_f32_e32 v0, v7, v7
	v_fmac_f32_e32 v0, v8, v8
	v_add_f32_e32 v0, v0, v4
	ds_bpermute_b32 v1, v205, v0
	v_cvt_pk_bf16_f32 v250, v5, v6
	v_cvt_pk_bf16_f32 v251, v7, v8
	s_nop 1
	v_permlane32_swap_b32_e32 v248, v250
	v_permlane32_swap_b32_e32 v249, v251
	global_store_dwordx4 v[252:253], v[248:251], off offset:2272
	s_and_saveexec_b64 s[6:7], s[46:47]
	s_cbranch_execz .LBB0_651
	s_waitcnt lgkmcnt(0)
	v_add_f32_e32 v2, v0, v1
	v_lshl_add_u64 v[0:1], v[64:65], 2, s[62:63]
	global_atomic_add_f32 v[0:1], v2, off
	s_branch .LBB0_651
